# attention loop: first QK K-fragment reads issued before the next tile LDS-DMA block
# speedup vs baseline: 1.0028x; 1.0028x over previous
.LBB0_511:
	s_lshl_b32 s100, s76, 14
	v_add3_u32 v236, s100, v221, v220
	ds_read_b128 v[192:195], v236
	ds_read_b128 v[196:199], v236 offset:8192
	v_add3_u32 v236, s100, v222, v220
	ds_read_b128 v[200:203], v236
	ds_read_b128 v[204:207], v236 offset:8192
	v_add3_u32 v236, s100, v223, v220
	ds_read_b128 v[240:243], v236
	ds_read_b128 v[244:247], v236 offset:8192
	v_add3_u32 v236, s100, v224, v220
	ds_read_b128 v[248:251], v236
	ds_read_b128 v[252:255], v236 offset:8192
	s_cmp_gt_u32 s86, 61
	s_cbranch_scc1 .LBB0_513
.LBB0_512:
	s_add_u32 s4, s84, s22
	s_addc_u32 s5, s85, s23
	s_lshl_b32 s24, s74, 14
	s_add_i32 s24, s75, s24
	s_mov_b32 m0, s24
	v_lshl_add_u64 v[234:235], v[212:213], 1, s[4:5]
	global_load_lds_dwordx4 v[234:235], off
	s_add_i32 m0, s24, 0x400
	v_lshl_add_u64 v[234:235], v[214:215], 1, s[4:5]
	global_load_lds_dwordx4 v[234:235], off
	s_add_u32 s4, s68, s22
	s_addc_u32 s5, s69, s23
	s_add_u32 s4, s4, 0x26840000
	s_addc_u32 s5, s5, 0
	s_lshl_b32 s24, s74, 15
	s_add_i32 s24, s77, s24
	s_mov_b32 m0, s24
	v_lshl_add_u64 v[234:235], v[216:217], 1, s[4:5]
	global_load_lds_dwordx4 v[234:235], off
	s_add_i32 m0, s24, 0x400
	v_lshl_add_u64 v[236:237], v[234:235], 0, s[8:9]
	global_load_lds_dwordx4 v[236:237], off
	s_add_i32 m0, s24, 0x800
	v_lshl_add_u64 v[236:237], v[234:235], 0, s[10:11]
	global_load_lds_dwordx4 v[236:237], off
	s_add_i32 m0, s24, 0xc00
	v_lshl_add_u64 v[234:235], v[234:235], 0, s[12:13]
	global_load_lds_dwordx4 v[234:235], off
.LBB0_513:
	s_waitcnt lgkmcnt(7)
	v_mfma_f32_32x32x16_bf16 v[144:159], v[192:195], v[160:163], 0
	s_waitcnt lgkmcnt(6)
	v_mfma_f32_32x32x16_bf16 v[128:143], v[196:199], v[160:163], 0
	v_add3_u32 v236, s100, v225, v220
	ds_read_b128 v[192:195], v236
	ds_read_b128 v[196:199], v236 offset:8192
	s_waitcnt lgkmcnt(7)
	v_mfma_f32_32x32x16_bf16 v[144:159], v[200:203], v[164:167], v[144:159]
	s_waitcnt lgkmcnt(6)
	v_mfma_f32_32x32x16_bf16 v[128:143], v[204:207], v[164:167], v[128:143]
	v_add3_u32 v236, s100, v227, v220
	ds_read_b128 v[200:203], v236
	ds_read_b128 v[204:207], v236 offset:8192
	s_waitcnt lgkmcnt(7)
	v_mfma_f32_32x32x16_bf16 v[144:159], v[240:243], v[168:171], v[144:159]
	s_waitcnt lgkmcnt(6)
	v_mfma_f32_32x32x16_bf16 v[128:143], v[244:247], v[168:171], v[128:143]
	v_add3_u32 v236, s100, v228, v220
	ds_read_b128 v[240:243], v236
	ds_read_b128 v[244:247], v236 offset:8192
	s_waitcnt lgkmcnt(7)
	v_mfma_f32_32x32x16_bf16 v[144:159], v[248:251], v[172:175], v[144:159]
	s_waitcnt lgkmcnt(6)
	v_mfma_f32_32x32x16_bf16 v[128:143], v[252:255], v[172:175], v[128:143]
	v_add3_u32 v236, s100, v229, v220
	ds_read_b128 v[248:251], v236
	ds_read_b128 v[252:255], v236 offset:8192
	s_waitcnt lgkmcnt(7)
	v_mfma_f32_32x32x16_bf16 v[144:159], v[192:195], v[176:179], v[144:159]
	s_waitcnt lgkmcnt(6)
	v_mfma_f32_32x32x16_bf16 v[128:143], v[196:199], v[176:179], v[128:143]
	s_waitcnt lgkmcnt(5)
	v_mfma_f32_32x32x16_bf16 v[144:159], v[200:203], v[180:183], v[144:159]
	s_waitcnt lgkmcnt(4)
	v_mfma_f32_32x32x16_bf16 v[128:143], v[204:207], v[180:183], v[128:143]
	s_waitcnt lgkmcnt(3)
	v_mfma_f32_32x32x16_bf16 v[144:159], v[240:243], v[184:187], v[144:159]
	s_waitcnt lgkmcnt(2)
	v_mfma_f32_32x32x16_bf16 v[128:143], v[244:247], v[184:187], v[128:143]
	s_waitcnt lgkmcnt(1)
	v_mfma_f32_32x32x16_bf16 v[144:159], v[248:251], v[188:191], v[144:159]
	s_waitcnt lgkmcnt(0)
	v_mfma_f32_32x32x16_bf16 v[128:143], v[252:255], v[188:191], v[128:143]
	s_nop 9
	v_max_f32_e32 v192, v144, v145
	v_max3_f32 v192, v192, v146, v147
	v_max3_f32 v192, v192, v148, v149
	v_max3_f32 v192, v192, v150, v151
	v_max3_f32 v192, v192, v152, v153
	v_max3_f32 v192, v192, v154, v155
	v_max3_f32 v192, v192, v156, v157
	v_max3_f32 v192, v192, v158, v159
	v_max3_f32 v192, v192, v128, v129
	v_max3_f32 v192, v192, v130, v131
	v_max3_f32 v192, v192, v132, v133
	v_max3_f32 v192, v192, v134, v135
	v_max3_f32 v192, v192, v136, v137
	v_max3_f32 v192, v192, v138, v139
	v_max3_f32 v192, v192, v140, v141
	v_max3_f32 v192, v192, v142, v143
	v_mov_b32_e32 v193, v192
	s_nop 1
	v_permlane32_swap_b32_e32 v192, v193
	v_max_f32_e32 v192, v192, v193
	v_sub_f32_e32 v193, v192, v231
	v_cmp_ge_f32_e32 vcc, s38, v193
	v_max_f32_e32 v234, v231, v192
	v_sub_f32_e32 v192, v231, v234
	v_mul_f32_e32 v192, 0x3e0293ee, v192
	v_exp_f32_e32 v192, v192
	s_cmp_eq_u64 vcc, exec
	s_cselect_b64 s[4:5], -1, 0
	v_cndmask_b32_e64 v233, v192, 1.0, s[4:5]
	v_cmp_gt_f32_e32 vcc, 1.0, v233
	s_cbranch_vccz .LBB0_517
	s_and_saveexec_b64 s[24:25], s[0:1]
	ds_write_b32 v226, v233 offset:128
	s_or_b64 exec, exec, s[24:25]
	s_waitcnt lgkmcnt(0)
	v_add_u32_e32 v192, s21, v210
	ds_read_b128 v[204:207], v192 offset:224
	ds_read_b128 v[200:203], v192 offset:192
	ds_read_b128 v[196:199], v192 offset:160
	ds_read_b128 v[192:195], v192 offset:128
	s_waitcnt lgkmcnt(3)
	v_pk_mul_f32 v[12:13], v[12:13], v[204:205]
	s_waitcnt lgkmcnt(2)
	v_pk_mul_f32 v[8:9], v[8:9], v[200:201]
	s_waitcnt lgkmcnt(1)
	v_pk_mul_f32 v[4:5], v[4:5], v[196:197]
	v_pk_mul_f32 v[14:15], v[14:15], v[206:207]
	v_pk_mul_f32 v[10:11], v[10:11], v[202:203]
	v_pk_mul_f32 v[6:7], v[6:7], v[198:199]
	s_waitcnt lgkmcnt(0)
	v_pk_mul_f32 v[2:3], v[2:3], v[194:195]
	v_pk_mul_f32 v[0:1], v[0:1], v[192:193]
	v_pk_mul_f32 v[124:125], v[124:125], v[204:205]
	v_pk_mul_f32 v[120:121], v[120:121], v[200:201]
	v_pk_mul_f32 v[116:117], v[116:117], v[196:197]
	v_pk_mul_f32 v[126:127], v[126:127], v[206:207]
	v_pk_mul_f32 v[122:123], v[122:123], v[202:203]
	v_pk_mul_f32 v[118:119], v[118:119], v[198:199]
	v_pk_mul_f32 v[114:115], v[114:115], v[194:195]
	v_pk_mul_f32 v[112:113], v[112:113], v[192:193]
	v_pk_mul_f32 v[108:109], v[108:109], v[204:205]
	v_pk_mul_f32 v[104:105], v[104:105], v[200:201]
	v_pk_mul_f32 v[100:101], v[100:101], v[196:197]
	v_pk_mul_f32 v[110:111], v[110:111], v[206:207]
	v_pk_mul_f32 v[106:107], v[106:107], v[202:203]
	v_pk_mul_f32 v[102:103], v[102:103], v[198:199]
	v_pk_mul_f32 v[98:99], v[98:99], v[194:195]
	v_pk_mul_f32 v[96:97], v[96:97], v[192:193]
	v_pk_mul_f32 v[92:93], v[92:93], v[204:205]
	v_pk_mul_f32 v[88:89], v[88:89], v[200:201]
	v_pk_mul_f32 v[84:85], v[84:85], v[196:197]
	v_pk_mul_f32 v[94:95], v[94:95], v[206:207]
	v_pk_mul_f32 v[90:91], v[90:91], v[202:203]
	v_pk_mul_f32 v[86:87], v[86:87], v[198:199]
	v_pk_mul_f32 v[82:83], v[82:83], v[194:195]
	v_pk_mul_f32 v[80:81], v[80:81], v[192:193]
	v_pk_mul_f32 v[76:77], v[76:77], v[204:205]
	v_pk_mul_f32 v[72:73], v[72:73], v[200:201]
	v_pk_mul_f32 v[68:69], v[68:69], v[196:197]
	v_pk_mul_f32 v[78:79], v[78:79], v[206:207]
	v_pk_mul_f32 v[74:75], v[74:75], v[202:203]
	v_pk_mul_f32 v[70:71], v[70:71], v[198:199]
	v_pk_mul_f32 v[66:67], v[66:67], v[194:195]
	v_pk_mul_f32 v[64:65], v[64:65], v[192:193]
	v_pk_mul_f32 v[60:61], v[60:61], v[204:205]
	v_pk_mul_f32 v[56:57], v[56:57], v[200:201]
	v_pk_mul_f32 v[52:53], v[52:53], v[196:197]
	v_pk_mul_f32 v[62:63], v[62:63], v[206:207]
	v_pk_mul_f32 v[58:59], v[58:59], v[202:203]
	v_pk_mul_f32 v[54:55], v[54:55], v[198:199]
	v_pk_mul_f32 v[50:51], v[50:51], v[194:195]
	v_pk_mul_f32 v[48:49], v[48:49], v[192:193]
	v_pk_mul_f32 v[44:45], v[44:45], v[204:205]
	v_pk_mul_f32 v[40:41], v[40:41], v[200:201]
	v_pk_mul_f32 v[36:37], v[36:37], v[196:197]
	v_pk_mul_f32 v[46:47], v[46:47], v[206:207]
	v_pk_mul_f32 v[42:43], v[42:43], v[202:203]
	v_pk_mul_f32 v[38:39], v[38:39], v[198:199]
	v_pk_mul_f32 v[34:35], v[34:35], v[194:195]
	v_pk_mul_f32 v[32:33], v[32:33], v[192:193]
	v_pk_mul_f32 v[28:29], v[28:29], v[204:205]
	v_pk_mul_f32 v[24:25], v[24:25], v[200:201]
	v_pk_mul_f32 v[20:21], v[20:21], v[196:197]
	v_pk_mul_f32 v[30:31], v[30:31], v[206:207]
	v_pk_mul_f32 v[26:27], v[26:27], v[202:203]
	v_pk_mul_f32 v[22:23], v[22:23], v[198:199]
	v_pk_mul_f32 v[18:19], v[18:19], v[194:195]
	v_pk_mul_f32 v[16:17], v[16:17], v[192:193]

.LBB0_520:
	s_waitcnt vmcnt(0) lgkmcnt(0)
	s_barrier
	s_branch .LBB0_511

.LBB0_904:
	s_lshl_b32 s100, s80, 14
	v_add3_u32 v236, s100, v221, v220
	ds_read_b128 v[192:195], v236
	ds_read_b128 v[196:199], v236 offset:8192
	v_add3_u32 v236, s100, v222, v220
	ds_read_b128 v[200:203], v236
	ds_read_b128 v[204:207], v236 offset:8192
	v_add3_u32 v236, s100, v223, v220
	ds_read_b128 v[240:243], v236
	ds_read_b128 v[244:247], v236 offset:8192
	v_add3_u32 v236, s100, v225, v220
	ds_read_b128 v[248:251], v236
	ds_read_b128 v[252:255], v236 offset:8192
	s_cmp_gt_u32 s86, 61
	s_cbranch_scc1 .LBB0_906
.LBB0_905:
	s_add_u32 s4, s84, s22
	s_addc_u32 s5, s85, s23
	s_lshl_b32 s24, s78, 14
	s_add_i32 s24, s79, s24
	s_mov_b32 m0, s24
	v_lshl_add_u64 v[234:235], v[212:213], 1, s[4:5]
	global_load_lds_dwordx4 v[234:235], off
	s_add_i32 m0, s24, 0x400
	v_lshl_add_u64 v[234:235], v[214:215], 1, s[4:5]
	global_load_lds_dwordx4 v[234:235], off
	s_add_u32 s4, s76, s22
	s_addc_u32 s5, s77, s23
	s_add_u32 s4, s4, 0x26840000
	s_addc_u32 s5, s5, 0
	s_lshl_b32 s24, s78, 15
	s_add_i32 s24, s81, s24
	s_mov_b32 m0, s24
	v_lshl_add_u64 v[234:235], v[216:217], 1, s[4:5]
	global_load_lds_dwordx4 v[234:235], off
	s_add_i32 m0, s24, 0x400
	v_lshl_add_u64 v[236:237], v[234:235], 0, s[8:9]
	global_load_lds_dwordx4 v[236:237], off
	s_add_i32 m0, s24, 0x800
	v_lshl_add_u64 v[236:237], v[234:235], 0, s[10:11]
	global_load_lds_dwordx4 v[236:237], off
	s_add_i32 m0, s24, 0xc00
	v_lshl_add_u64 v[234:235], v[234:235], 0, s[12:13]
	global_load_lds_dwordx4 v[234:235], off
.LBB0_906:
	s_waitcnt lgkmcnt(7)
	v_mfma_f32_32x32x16_bf16 v[144:159], v[192:195], v[160:163], 0
	s_waitcnt lgkmcnt(6)
	v_mfma_f32_32x32x16_bf16 v[128:143], v[196:199], v[160:163], 0
	v_add3_u32 v236, s100, v226, v220
	ds_read_b128 v[192:195], v236
	ds_read_b128 v[196:199], v236 offset:8192
	s_waitcnt lgkmcnt(7)
	v_mfma_f32_32x32x16_bf16 v[144:159], v[200:203], v[164:167], v[144:159]
	s_waitcnt lgkmcnt(6)
	v_mfma_f32_32x32x16_bf16 v[128:143], v[204:207], v[164:167], v[128:143]
	v_add3_u32 v236, s100, v227, v220
	ds_read_b128 v[200:203], v236
	ds_read_b128 v[204:207], v236 offset:8192
	s_waitcnt lgkmcnt(7)
	v_mfma_f32_32x32x16_bf16 v[144:159], v[240:243], v[168:171], v[144:159]
	s_waitcnt lgkmcnt(6)
	v_mfma_f32_32x32x16_bf16 v[128:143], v[244:247], v[168:171], v[128:143]
	v_add3_u32 v236, s100, v228, v220
	ds_read_b128 v[240:243], v236
	ds_read_b128 v[244:247], v236 offset:8192
	s_waitcnt lgkmcnt(7)
	v_mfma_f32_32x32x16_bf16 v[144:159], v[248:251], v[172:175], v[144:159]
	s_waitcnt lgkmcnt(6)
	v_mfma_f32_32x32x16_bf16 v[128:143], v[252:255], v[172:175], v[128:143]
	v_add3_u32 v236, s100, v229, v220
	ds_read_b128 v[248:251], v236
	ds_read_b128 v[252:255], v236 offset:8192
	s_waitcnt lgkmcnt(7)
	v_mfma_f32_32x32x16_bf16 v[144:159], v[192:195], v[176:179], v[144:159]
	s_waitcnt lgkmcnt(6)
	v_mfma_f32_32x32x16_bf16 v[128:143], v[196:199], v[176:179], v[128:143]
	s_waitcnt lgkmcnt(5)
	v_mfma_f32_32x32x16_bf16 v[144:159], v[200:203], v[180:183], v[144:159]
	s_waitcnt lgkmcnt(4)
	v_mfma_f32_32x32x16_bf16 v[128:143], v[204:207], v[180:183], v[128:143]
	s_waitcnt lgkmcnt(3)
	v_mfma_f32_32x32x16_bf16 v[144:159], v[240:243], v[184:187], v[144:159]
	s_waitcnt lgkmcnt(2)
	v_mfma_f32_32x32x16_bf16 v[128:143], v[244:247], v[184:187], v[128:143]
	s_waitcnt lgkmcnt(1)
	v_mfma_f32_32x32x16_bf16 v[144:159], v[248:251], v[188:191], v[144:159]
	s_waitcnt lgkmcnt(0)
	v_mfma_f32_32x32x16_bf16 v[128:143], v[252:255], v[188:191], v[128:143]
	v_max_f32_e32 v194, v231, v231
	s_nop 9
	v_max_f32_e32 v192, v144, v145
	v_max3_f32 v192, v192, v146, v147
	v_max3_f32 v192, v192, v148, v149
	v_max3_f32 v192, v192, v150, v151
	v_max3_f32 v192, v192, v152, v153
	v_max3_f32 v192, v192, v154, v155
	v_max3_f32 v192, v192, v156, v157
	v_max3_f32 v192, v192, v158, v159
	v_max3_f32 v192, v192, v128, v129
	v_max3_f32 v192, v192, v130, v131
	v_max3_f32 v192, v192, v132, v133
	v_max3_f32 v192, v192, v134, v135
	v_max3_f32 v192, v192, v136, v137
	v_max3_f32 v192, v192, v138, v139
	v_max3_f32 v192, v192, v140, v141
	v_max3_f32 v192, v192, v142, v143
	v_mov_b32_e32 v193, v192
	s_nop 1
	v_permlane32_swap_b32_e32 v192, v193
	v_max_f32_e32 v192, v192, v193
	v_max_f32_e32 v234, v194, v192
	v_sub_f32_e32 v193, v192, v231
	v_sub_f32_e32 v192, v231, v234
	v_mul_f32_e32 v192, 0x3e0293ee, v192
	v_exp_f32_e32 v192, v192
	v_cmp_ge_f32_e32 vcc, s42, v193
	s_cmp_eq_u64 vcc, exec
	s_cselect_b64 s[4:5], -1, 0
	v_cndmask_b32_e64 v233, v192, 1.0, s[4:5]
	v_cmp_gt_f32_e32 vcc, 1.0, v233
	s_cbranch_vccz .LBB0_910
	s_and_saveexec_b64 s[24:25], s[0:1]
	ds_write_b32 v224, v233 offset:128
	s_or_b64 exec, exec, s[24:25]
	s_waitcnt lgkmcnt(0)
	v_add_u32_e32 v192, s21, v210
	ds_read_b128 v[204:207], v192 offset:224
	ds_read_b128 v[200:203], v192 offset:192
	ds_read_b128 v[196:199], v192 offset:160
	ds_read_b128 v[192:195], v192 offset:128
	s_waitcnt lgkmcnt(3)
	v_pk_mul_f32 v[12:13], v[12:13], v[204:205]
	s_waitcnt lgkmcnt(2)
	v_pk_mul_f32 v[8:9], v[8:9], v[200:201]
	s_waitcnt lgkmcnt(1)
	v_pk_mul_f32 v[4:5], v[4:5], v[196:197]
	v_pk_mul_f32 v[14:15], v[14:15], v[206:207]
	v_pk_mul_f32 v[10:11], v[10:11], v[202:203]
	v_pk_mul_f32 v[6:7], v[6:7], v[198:199]
	s_waitcnt lgkmcnt(0)
	v_pk_mul_f32 v[2:3], v[2:3], v[194:195]
	v_pk_mul_f32 v[0:1], v[0:1], v[192:193]
	v_pk_mul_f32 v[124:125], v[124:125], v[204:205]
	v_pk_mul_f32 v[120:121], v[120:121], v[200:201]
	v_pk_mul_f32 v[116:117], v[116:117], v[196:197]
	v_pk_mul_f32 v[126:127], v[126:127], v[206:207]
	v_pk_mul_f32 v[122:123], v[122:123], v[202:203]
	v_pk_mul_f32 v[118:119], v[118:119], v[198:199]
	v_pk_mul_f32 v[114:115], v[114:115], v[194:195]
	v_pk_mul_f32 v[112:113], v[112:113], v[192:193]
	v_pk_mul_f32 v[108:109], v[108:109], v[204:205]
	v_pk_mul_f32 v[104:105], v[104:105], v[200:201]
	v_pk_mul_f32 v[100:101], v[100:101], v[196:197]
	v_pk_mul_f32 v[110:111], v[110:111], v[206:207]
	v_pk_mul_f32 v[106:107], v[106:107], v[202:203]
	v_pk_mul_f32 v[102:103], v[102:103], v[198:199]
	v_pk_mul_f32 v[98:99], v[98:99], v[194:195]
	v_pk_mul_f32 v[96:97], v[96:97], v[192:193]
	v_pk_mul_f32 v[92:93], v[92:93], v[204:205]
	v_pk_mul_f32 v[88:89], v[88:89], v[200:201]
	v_pk_mul_f32 v[84:85], v[84:85], v[196:197]
	v_pk_mul_f32 v[94:95], v[94:95], v[206:207]
	v_pk_mul_f32 v[90:91], v[90:91], v[202:203]
	v_pk_mul_f32 v[86:87], v[86:87], v[198:199]
	v_pk_mul_f32 v[82:83], v[82:83], v[194:195]
	v_pk_mul_f32 v[80:81], v[80:81], v[192:193]
	v_pk_mul_f32 v[76:77], v[76:77], v[204:205]
	v_pk_mul_f32 v[72:73], v[72:73], v[200:201]
	v_pk_mul_f32 v[68:69], v[68:69], v[196:197]
	v_pk_mul_f32 v[78:79], v[78:79], v[206:207]
	v_pk_mul_f32 v[74:75], v[74:75], v[202:203]
	v_pk_mul_f32 v[70:71], v[70:71], v[198:199]
	v_pk_mul_f32 v[66:67], v[66:67], v[194:195]
	v_pk_mul_f32 v[64:65], v[64:65], v[192:193]
	v_pk_mul_f32 v[60:61], v[60:61], v[204:205]
	v_pk_mul_f32 v[56:57], v[56:57], v[200:201]
	v_pk_mul_f32 v[52:53], v[52:53], v[196:197]
	v_pk_mul_f32 v[62:63], v[62:63], v[206:207]
	v_pk_mul_f32 v[58:59], v[58:59], v[202:203]
	v_pk_mul_f32 v[54:55], v[54:55], v[198:199]
	v_pk_mul_f32 v[50:51], v[50:51], v[194:195]
	v_pk_mul_f32 v[48:49], v[48:49], v[192:193]
	v_pk_mul_f32 v[44:45], v[44:45], v[204:205]
	v_pk_mul_f32 v[40:41], v[40:41], v[200:201]
	v_pk_mul_f32 v[36:37], v[36:37], v[196:197]
	v_pk_mul_f32 v[46:47], v[46:47], v[206:207]
	v_pk_mul_f32 v[42:43], v[42:43], v[202:203]
	v_pk_mul_f32 v[38:39], v[38:39], v[198:199]
	v_pk_mul_f32 v[34:35], v[34:35], v[194:195]
	v_pk_mul_f32 v[32:33], v[32:33], v[192:193]
	v_pk_mul_f32 v[28:29], v[28:29], v[204:205]
	v_pk_mul_f32 v[24:25], v[24:25], v[200:201]
	v_pk_mul_f32 v[20:21], v[20:21], v[196:197]
	v_pk_mul_f32 v[30:31], v[30:31], v[206:207]
	v_pk_mul_f32 v[26:27], v[26:27], v[202:203]
	v_pk_mul_f32 v[22:23], v[22:23], v[198:199]
	v_pk_mul_f32 v[18:19], v[18:19], v[194:195]
	v_pk_mul_f32 v[16:17], v[16:17], v[192:193]
